# P0 input-row loads: cache policy sc1 nt (streaming, not retained) instead of nt alone
# speedup vs baseline: 1.0137x; 1.0037x over previous
; DI unsigned pk_bf16(float lo, float hi) { f32x2 v = {lo, hi}; bf16x2_t b = __builtin_convertvector(v, bf16x2_t); return __builtin_bit_cast(unsigned, b); }
; DI void p0_row(const Params& P, int row, const f32x4 (&v)[4], bf16_t* U, float* LOGF, const LAS f32x4* wf, int lane) {
;     float ss = 0.f;
; #pragma unroll
;     for (int jj = 0; jj < 4; ++jj) { ss += (v[jj].x * v[jj].x + v[jj].y * v[jj].y) + (v[jj].z * v[jj].z + v[jj].w * v[jj].w); }
;     const float rstd = 1.f / sqrtf(wave_sum(ss) * (1.f / DM) + RMS_EPS);
;     u32x2* uo = (u32x2*)(U + (size_t)row * DM) + lane;
;     float acc[8];
; #pragma unroll
;     for (int j = 0; j < 8; ++j) acc[j] = 0.f;
; #pragma unroll
;     for (int jj = 0; jj < 4; ++jj) { const f32x4 g0 = *((const f32x4*)P.norm_g + lane + 64 * jj); const f32x4 y = v[jj] * rstd * g0;
;         u32x2 w; w.x = pk_bf16(y.x, y.y); w.y = pk_bf16(y.z, y.w); uo[64 * jj] = w;
; #pragma unroll
;         for (int e = 0; e < 4; ++e) { const f32x4 wa = wf[((jj * 4 + e) * 2 + 0) * 64 + lane], wb = wf[((jj * 4 + e) * 2 + 1) * 64 + lane]; const float ye = y[e];
;             acc[0] += ye * wa.x; acc[1] += ye * wa.y; acc[2] += ye * wa.z; acc[3] += ye * wa.w; acc[4] += ye * wb.x; acc[5] += ye * wb.y; acc[6] += ye * wb.z; acc[7] += ye * wb.w; } }
; __global__ void __launch_bounds__(512) fwd_kernel(Params P) {
;     ...
;         for (int row0 = 4 * gw; row0 < MT; row0 += 4 * NGW) {
;             f32x4 xv[4][4];
; #pragma unroll
;             for (int b = 0; b < 4; ++b)
; #pragma unroll
;                 for (int jj = 0; jj < 4; ++jj) xv[b][jj] = ((const f32x4*)(P.x + (size_t)(row0 + b) * DM) + lane)[64 * jj];
; #pragma unroll
;             for (int b = 0; b < 4; ++b) p0_row(P, row0 + b, xv[b], U, LOGF, wf, lane);
.LBB0_222:
	global_load_dwordx4 v[184:187], v[202:203], off sc1 nt
	global_load_dwordx4 v[188:191], v[202:203], off offset:1024 sc1 nt
	global_load_dwordx4 v[176:179], v[202:203], off offset:2048 sc1 nt
	global_load_dwordx4 v[180:183], v[202:203], off offset:3072 sc1 nt
	global_load_dwordx4 v[222:225], v[196:197], off
	s_waitcnt vmcnt(4)
	v_pk_mul_f32 v[128:129], v[186:187], v[186:187]
	v_pk_mul_f32 v[130:131], v[184:185], v[184:185]
	s_waitcnt vmcnt(3) lgkmcnt(7)
	v_pk_mul_f32 v[132:133], v[190:191], v[190:191]
	s_waitcnt lgkmcnt(6)
	v_pk_mul_f32 v[134:135], v[188:189], v[188:189]
	s_waitcnt lgkmcnt(2)
	v_pk_mov_b32 v[140:141], v[130:131], v[128:129] op_sel:[1,0]
	v_mov_b32_e32 v131, v129
	v_pk_mov_b32 v[128:129], v[134:135], v[132:133] op_sel:[1,0]
	v_mov_b32_e32 v135, v133
	s_waitcnt vmcnt(2)
	v_mul_f32_e32 v136, v177, v177
	s_waitcnt vmcnt(1)
	v_mul_f32_e32 v139, v182, v182
	v_mul_f32_e32 v138, v179, v179
	v_pk_add_f32 v[130:131], v[140:141], v[130:131]
	v_pk_add_f32 v[128:129], v[128:129], v[134:135]
	s_waitcnt lgkmcnt(1)
	v_mul_f32_e32 v142, v183, v183
	s_waitcnt lgkmcnt(0)
	v_mul_f32_e32 v143, v180, v180
	v_mul_f32_e32 v144, v181, v181
	v_pk_fma_f32 v[132:133], v[176:177], v[176:177], v[136:137] op_sel_hi:[1,1,0]
	v_pk_fma_f32 v[136:137], v[178:179], v[178:179], v[138:139] op_sel_hi:[1,1,0]
	v_pk_add_f32 v[130:131], v[130:131], v[130:131] op_sel:[0,1] op_sel_hi:[1,0]
	v_pk_add_f32 v[128:129], v[128:129], v[128:129] op_sel:[0,1] op_sel_hi:[1,0]
	v_mov_b32_e32 v133, v139
	v_mov_b32_e32 v137, v142
	v_mov_b32_e32 v131, v143
	v_mov_b32_e32 v129, v144
	v_pk_add_f32 v[132:133], v[132:133], v[136:137]
	v_pk_add_f32 v[128:129], v[130:131], v[128:129]
	s_nop 0
	v_pk_add_f32 v[128:129], v[128:129], v[132:133]
	s_nop 0
	v_add_f32_e32 v128, v128, v129
	ds_bpermute_b32 v129, v193, v128
	s_waitcnt lgkmcnt(0)
	v_add_f32_e32 v129, v128, v129
	ds_bpermute_b32 v130, v195, v129
	v_add_co_u32_e32 v128, vcc, 0x1000, v202
	s_mov_b64 s[0:1], vcc
	s_waitcnt lgkmcnt(0)
	v_add_f32_e32 v131, v129, v130
	ds_bpermute_b32 v132, v211, v131
	v_add_co_u32_e32 v130, vcc, 0x2000, v202
	s_mov_b64 s[22:23], vcc
	v_addc_co_u32_e64 v129, vcc, 0, v203, s[0:1]
	s_waitcnt lgkmcnt(0)
	v_add_f32_e32 v132, v131, v132
	ds_bpermute_b32 v133, v212, v132
	global_load_dwordx4 v[172:175], v[128:129], off sc1 nt
	global_load_dwordx4 v[168:171], v[128:129], off offset:1024 sc1 nt
	global_load_dwordx4 v[164:167], v[128:129], off offset:2048 sc1 nt
	global_load_dwordx4 v[160:163], v[128:129], off offset:3072 sc1 nt
	v_add_co_u32_e32 v206, vcc, 0x3000, v202
	v_addc_co_u32_e64 v131, s[0:1], 0, v203, s[22:23]
	s_waitcnt lgkmcnt(0)
	v_add_f32_e32 v132, v132, v133
	ds_bpermute_b32 v133, v213, v132
	v_addc_co_u32_e32 v207, vcc, 0, v203, vcc
	global_load_dwordx4 v[156:159], v[130:131], off sc1 nt
	global_load_dwordx4 v[152:155], v[130:131], off offset:1024 sc1 nt
	global_load_dwordx4 v[148:151], v[130:131], off offset:2048 sc1 nt
	global_load_dwordx4 v[144:147], v[130:131], off offset:3072 sc1 nt
	global_load_dwordx4 v[140:143], v[206:207], off sc1 nt
	global_load_dwordx4 v[136:139], v[206:207], off offset:1024 sc1 nt
	s_waitcnt lgkmcnt(0)
	v_add_f32_e32 v128, v132, v133
	ds_bpermute_b32 v129, v214, v128
	s_waitcnt lgkmcnt(0)
	v_add_f32_e32 v128, v128, v129
	v_fmamk_f32 v128, v128, 0x3a800000, v215
	v_mul_f32_e32 v129, 0x4f800000, v128
	v_cmp_gt_f32_e32 vcc, s3, v128
	s_nop 1
	v_cndmask_b32_e32 v128, v128, v129, vcc
	v_sqrt_f32_e32 v129, v128
	s_nop 0
	v_add_u32_e32 v130, -1, v129
	v_add_u32_e32 v131, 1, v129
	v_fma_f32 v132, -v130, v129, v128
	v_fma_f32 v133, -v131, v129, v128
	v_cmp_ge_f32_e64 s[0:1], 0, v132
	s_nop 1
	v_cndmask_b32_e64 v129, v129, v130, s[0:1]
	v_cmp_lt_f32_e64 s[0:1], 0, v133
	s_nop 1
	v_cndmask_b32_e64 v129, v129, v131, s[0:1]
	v_mul_f32_e32 v130, 0x37800000, v129
	v_cndmask_b32_e32 v129, v129, v130, vcc
	v_cmp_class_f32_e32 vcc, v128, v216
	s_nop 1
	v_cndmask_b32_e32 v205, v129, v128, vcc
	v_div_scale_f32 v208, s[0:1], v205, v205, 1.0
	v_rcp_f32_e32 v209, v208
	global_load_dwordx4 v[132:135], v[206:207], off offset:2048 sc1 nt
	global_load_dwordx4 v[128:131], v[206:207], off offset:3072 sc1 nt
	v_div_scale_f32 v206, vcc, 1.0, v205, 1.0
	v_fma_f32 v207, -v208, v209, 1.0
	v_fmac_f32_e32 v209, v207, v209
	v_mul_f32_e32 v207, v206, v209
	v_fma_f32 v210, -v208, v207, v206
	v_fmac_f32_e32 v207, v210, v209
	v_fma_f32 v206, -v208, v207, v206
	v_div_fmas_f32 v206, v206, v209, v207
	v_div_fixup_f32 v210, v206, v205, 1.0
	v_pk_mul_f32 v[184:185], v[184:185], v[210:211] op_sel_hi:[1,0]
	v_pk_mul_f32 v[186:187], v[186:187], v[210:211] op_sel_hi:[1,0]
	s_waitcnt vmcnt(12)
	v_pk_mul_f32 v[208:209], v[222:223], v[184:185]
	v_pk_mul_f32 v[206:207], v[224:225], v[186:187]
	v_cvt_pk_bf16_f32 v184, v208, v209
	v_cvt_pk_bf16_f32 v185, v206, v207
	global_store_dwordx2 v[200:201], v[184:185], off
	global_load_dwordx4 v[184:187], v[196:197], off offset:1024
	v_pk_mul_f32 v[222:223], v[188:189], v[210:211] op_sel_hi:[1,0]
	v_pk_mul_f32 v[188:189], v[190:191], v[210:211] op_sel_hi:[1,0]
	v_pk_mul_f32 v[176:177], v[176:177], v[210:211] op_sel_hi:[1,0]
	v_pk_mul_f32 v[178:179], v[178:179], v[210:211] op_sel_hi:[1,0]
	v_pk_mul_f32 v[180:181], v[180:181], v[210:211] op_sel_hi:[1,0]
	v_pk_mul_f32 v[182:183], v[182:183], v[210:211] op_sel_hi:[1,0]
	v_fma_f32 v205, v0, v208, 0
	v_fma_f32 v210, v1, v208, 0
	v_fma_f32 v221, v2, v208, 0
	v_fma_f32 v224, v5, v208, 0
	v_fma_f32 v225, v6, v208, 0
	v_fmac_f32_e32 v205, v8, v209
	v_fmac_f32_e32 v210, v9, v209
	v_fmac_f32_e32 v221, v10, v209
	v_fmac_f32_e32 v224, v13, v209
	v_fmac_f32_e32 v225, v14, v209
	v_fmac_f32_e32 v205, v16, v206
	v_fmac_f32_e32 v210, v17, v206
	v_fmac_f32_e32 v221, v18, v206
	v_fmac_f32_e32 v224, v21, v206
	v_fmac_f32_e32 v225, v22, v206
	v_fmac_f32_e32 v205, v24, v207
	v_fmac_f32_e32 v210, v25, v207
	v_fmac_f32_e32 v221, v26, v207
	v_fmac_f32_e32 v224, v29, v207
	v_fmac_f32_e32 v225, v30, v207
	s_ashr_i32 s0, s28, 11
	s_waitcnt vmcnt(0)
; DI unsigned pk_bf16(float lo, float hi) { f32x2 v = {lo, hi}; bf16x2_t b = __builtin_convertvector(v, bf16x2_t); return __builtin_bit_cast(unsigned, b); }
; DI void p0_row(const Params& P, int row, const f32x4 (&v)[4], bf16_t* U, float* LOGF, const LAS f32x4* wf, int lane) {
;     ...
;     for (int jj = 0; jj < 4; ++jj) { const f32x4 g0 = *((const f32x4*)P.norm_g + lane + 64 * jj); const f32x4 y = v[jj] * rstd * g0;
;         u32x2 w; w.x = pk_bf16(y.x, y.y); w.y = pk_bf16(y.z, y.w); uo[64 * jj] = w;
; #pragma unroll
;         for (int e = 0; e < 4; ++e) { const f32x4 wa = wf[((jj * 4 + e) * 2 + 0) * 64 + lane], wb = wf[((jj * 4 + e) * 2 + 1) * 64 + lane]; const float ye = y[e];
;             acc[0] += ye * wa.x; acc[1] += ye * wa.y; acc[2] += ye * wa.z; acc[3] += ye * wa.w; acc[4] += ye * wb.x; acc[5] += ye * wb.y; acc[6] += ye * wb.z; acc[7] += ye * wb.w; } }
;     float mine = 0.f;
; #pragma unroll
;     for (int j = 0; j < 8; ++j) { const float s = wave_sum(acc[j]); if (lane == j) mine = s; }
	v_pk_mul_f32 v[188:189], v[188:189], v[186:187]
	v_pk_mul_f32 v[190:191], v[222:223], v[184:185]
	v_cvt_pk_bf16_f32 v185, v188, v189
	v_cvt_pk_bf16_f32 v184, v190, v191
	global_store_dwordx2 v[200:201], v[184:185], off offset:512
	global_load_dwordx4 v[184:187], v[196:197], off offset:2048
	v_fma_f32 v222, v3, v208, 0
	v_fma_f32 v223, v4, v208, 0
	v_fma_f32 v208, v7, v208, 0
	v_fmac_f32_e32 v222, v11, v209
	v_fmac_f32_e32 v223, v12, v209
	v_fmac_f32_e32 v208, v15, v209
	v_fmac_f32_e32 v222, v19, v206
	v_fmac_f32_e32 v223, v20, v206
	v_fmac_f32_e32 v208, v23, v206
	v_fmac_f32_e32 v222, v27, v207
	v_fmac_f32_e32 v223, v28, v207
	v_fmac_f32_e32 v208, v31, v207
	v_fmac_f32_e32 v205, v190, v32
	v_fmac_f32_e32 v210, v190, v33
	v_fmac_f32_e32 v221, v190, v34
	v_fmac_f32_e32 v222, v190, v35
	v_fmac_f32_e32 v223, v190, v36
	v_fmac_f32_e32 v224, v190, v37
	v_fmac_f32_e32 v225, v190, v38
	v_fmac_f32_e32 v208, v190, v39
	v_fmac_f32_e32 v205, v191, v40
	v_fmac_f32_e32 v210, v191, v41
	v_fmac_f32_e32 v221, v191, v42
	v_fmac_f32_e32 v222, v191, v43
	v_fmac_f32_e32 v223, v191, v44
	v_fmac_f32_e32 v224, v191, v45
	v_fmac_f32_e32 v225, v191, v46
	v_fmac_f32_e32 v208, v191, v47
	v_fmac_f32_e32 v205, v188, v48
	v_fmac_f32_e32 v210, v188, v49
	v_fmac_f32_e32 v221, v188, v50
	v_fmac_f32_e32 v222, v188, v51
	v_fmac_f32_e32 v223, v188, v52
	v_fmac_f32_e32 v224, v188, v53
	v_fmac_f32_e32 v225, v188, v54
	v_fmac_f32_e32 v208, v188, v55
	v_fmac_f32_e32 v205, v189, v56
	v_fmac_f32_e32 v210, v189, v57
	v_fmac_f32_e32 v221, v189, v58
	v_fmac_f32_e32 v222, v189, v59
	v_fmac_f32_e32 v223, v189, v60
	v_fmac_f32_e32 v224, v189, v61
	v_fmac_f32_e32 v225, v189, v62
	v_fmac_f32_e32 v208, v189, v63
	s_waitcnt vmcnt(0)
	v_pk_mul_f32 v[186:187], v[178:179], v[186:187]
	v_pk_mul_f32 v[184:185], v[176:177], v[184:185]
	v_cvt_pk_bf16_f32 v177, v186, v187
	v_cvt_pk_bf16_f32 v176, v184, v185
	global_store_dwordx2 v[200:201], v[176:177], off offset:1024
	global_load_dwordx4 v[176:179], v[196:197], off offset:3072
	v_fmac_f32_e32 v205, v184, v64
	v_fmac_f32_e32 v210, v184, v65
	v_fmac_f32_e32 v221, v184, v66
	v_fmac_f32_e32 v222, v184, v67
	v_fmac_f32_e32 v223, v184, v68
	v_fmac_f32_e32 v224, v184, v69
	v_fmac_f32_e32 v225, v184, v70
	v_fmac_f32_e32 v208, v184, v71
	v_fmac_f32_e32 v205, v185, v72
	v_fmac_f32_e32 v210, v185, v73
	v_fmac_f32_e32 v221, v185, v74
	v_fmac_f32_e32 v222, v185, v75
	v_fmac_f32_e32 v223, v185, v76
	v_fmac_f32_e32 v224, v185, v77
	v_fmac_f32_e32 v225, v185, v78
	v_fmac_f32_e32 v208, v185, v79
	v_fmac_f32_e32 v205, v186, v80
	v_fmac_f32_e32 v210, v186, v81
	v_fmac_f32_e32 v221, v186, v82
	v_fmac_f32_e32 v222, v186, v83
	v_fmac_f32_e32 v223, v186, v84
	v_fmac_f32_e32 v224, v186, v85
	v_fmac_f32_e32 v225, v186, v86
	v_fmac_f32_e32 v208, v186, v87
	v_fmac_f32_e32 v205, v187, v88
	v_fmac_f32_e32 v210, v187, v89
	v_fmac_f32_e32 v221, v187, v90
	v_fmac_f32_e32 v222, v187, v91
	v_fmac_f32_e32 v223, v187, v92
	v_fmac_f32_e32 v224, v187, v93
	v_fmac_f32_e32 v225, v187, v94
	v_fmac_f32_e32 v208, v187, v95
	s_waitcnt vmcnt(0)
	v_pk_mul_f32 v[176:177], v[180:181], v[176:177]
	s_nop 0
	v_fmac_f32_e32 v205, v176, v96
	v_fmac_f32_e32 v210, v176, v97
	v_fmac_f32_e32 v221, v176, v98
	v_fmac_f32_e32 v222, v176, v99
	v_fmac_f32_e32 v223, v176, v100
	v_fmac_f32_e32 v224, v176, v101
	v_fmac_f32_e32 v225, v176, v102
	v_fmac_f32_e32 v208, v176, v103
	v_pk_mul_f32 v[178:179], v[182:183], v[178:179]
	v_fmac_f32_e32 v205, v177, v104
	v_fmac_f32_e32 v210, v177, v105
	v_fmac_f32_e32 v221, v177, v106
	v_fmac_f32_e32 v222, v177, v107
	v_fmac_f32_e32 v223, v177, v108
	v_fmac_f32_e32 v224, v177, v109
	v_fmac_f32_e32 v225, v177, v110
	v_fmac_f32_e32 v208, v177, v111
	v_fmac_f32_e32 v205, v178, v112
	v_fmac_f32_e32 v210, v178, v113
	v_fmac_f32_e32 v221, v178, v114
	v_fmac_f32_e32 v222, v178, v115
	v_fmac_f32_e32 v223, v178, v116
	v_fmac_f32_e32 v224, v178, v117
	v_fmac_f32_e32 v225, v178, v118
	v_fmac_f32_e32 v208, v178, v119
	v_cvt_pk_bf16_f32 v180, v176, v177
	v_cvt_pk_bf16_f32 v181, v178, v179
	v_fmac_f32_e32 v205, v179, v120
	v_fmac_f32_e32 v210, v179, v121
	v_fmac_f32_e32 v221, v179, v122
	v_fmac_f32_e32 v222, v179, v123
	v_fmac_f32_e32 v223, v179, v124
	v_fmac_f32_e32 v224, v179, v125
	v_fmac_f32_e32 v225, v179, v126
	v_fmac_f32_e32 v208, v179, v127
	global_store_dwordx2 v[200:201], v[180:181], off offset:1536
	ds_bpermute_b32 v176, v193, v205
	ds_bpermute_b32 v177, v193, v210
	ds_bpermute_b32 v178, v193, v221
	ds_bpermute_b32 v179, v193, v222
	ds_bpermute_b32 v180, v193, v223
	ds_bpermute_b32 v181, v193, v224
	ds_bpermute_b32 v182, v193, v225
	ds_bpermute_b32 v183, v193, v208
	s_waitcnt lgkmcnt(7)
	v_add_f32_e32 v176, v205, v176
	s_waitcnt lgkmcnt(6)
	v_add_f32_e32 v177, v210, v177
	s_waitcnt lgkmcnt(5)
	v_add_f32_e32 v178, v221, v178
	s_waitcnt lgkmcnt(4)
	v_add_f32_e32 v179, v222, v179
	s_waitcnt lgkmcnt(3)
	v_add_f32_e32 v180, v223, v180
	s_waitcnt lgkmcnt(2)
	v_add_f32_e32 v181, v224, v181
	s_waitcnt lgkmcnt(1)
	v_add_f32_e32 v182, v225, v182
	s_waitcnt lgkmcnt(0)
	v_add_f32_e32 v183, v208, v183
	ds_bpermute_b32 v184, v195, v176
	ds_bpermute_b32 v185, v195, v177
	ds_bpermute_b32 v186, v195, v178
	ds_bpermute_b32 v187, v195, v179
	ds_bpermute_b32 v188, v195, v180
	ds_bpermute_b32 v189, v195, v181
	ds_bpermute_b32 v190, v195, v182
	ds_bpermute_b32 v191, v195, v183
	s_waitcnt lgkmcnt(7)
	v_add_f32_e32 v176, v176, v184
	s_waitcnt lgkmcnt(6)
	v_add_f32_e32 v177, v177, v185
	s_waitcnt lgkmcnt(5)
	v_add_f32_e32 v178, v178, v186
	s_waitcnt lgkmcnt(4)
	v_add_f32_e32 v179, v179, v187
	s_waitcnt lgkmcnt(3)
	v_add_f32_e32 v180, v180, v188
	s_waitcnt lgkmcnt(2)
	v_add_f32_e32 v181, v181, v189
	s_waitcnt lgkmcnt(1)
; DI float log_sigmoid_f(float z) { return fminf(z, 0.f) - log1pf(__expf(-fabsf(z))); }
; DI float wave_sum(float v) {
;     ...
;     for (int o = 1; o < 64; o <<= 1) v += __shfl_xor(v, o);
; DI void p0_row(const Params& P, int row, const f32x4 (&v)[4], bf16_t* U, float* LOGF, const LAS f32x4* wf, int lane) {
;     ...
;     for (int j = 0; j < 8; ++j) { const float s = wave_sum(acc[j]); if (lane == j) mine = s; }
;     if (lane < 8) { const int b = row >> 14, t = row & (SEQ - 1); LOGF[(size_t)(b * 8 + lane) * SEQ + t] = log_sigmoid_f(mine + P.b_f[lane]); }
	v_add_f32_e32 v182, v182, v190
	s_waitcnt lgkmcnt(0)
	v_add_f32_e32 v183, v183, v191
	ds_bpermute_b32 v184, v211, v176
	ds_bpermute_b32 v185, v211, v177
	ds_bpermute_b32 v186, v211, v178
	ds_bpermute_b32 v187, v211, v179
	ds_bpermute_b32 v188, v211, v180
	ds_bpermute_b32 v189, v211, v181
	ds_bpermute_b32 v190, v211, v182
	ds_bpermute_b32 v191, v211, v183
	s_waitcnt lgkmcnt(7)
	v_add_f32_e32 v176, v176, v184
	s_waitcnt lgkmcnt(6)
	v_add_f32_e32 v177, v177, v185
	s_waitcnt lgkmcnt(5)
	v_add_f32_e32 v178, v178, v186
	s_waitcnt lgkmcnt(4)
	v_add_f32_e32 v179, v179, v187
	s_waitcnt lgkmcnt(3)
	v_add_f32_e32 v180, v180, v188
	s_waitcnt lgkmcnt(2)
	v_add_f32_e32 v181, v181, v189
	s_waitcnt lgkmcnt(1)
	v_add_f32_e32 v182, v182, v190
	s_waitcnt lgkmcnt(0)
	v_add_f32_e32 v183, v183, v191
	ds_bpermute_b32 v184, v212, v176
	ds_bpermute_b32 v185, v212, v177
	ds_bpermute_b32 v186, v212, v178
	ds_bpermute_b32 v187, v212, v179
	ds_bpermute_b32 v188, v212, v180
	ds_bpermute_b32 v189, v212, v181
	ds_bpermute_b32 v190, v212, v182
	ds_bpermute_b32 v191, v212, v183
	s_waitcnt lgkmcnt(7)
	v_add_f32_e32 v176, v176, v184
	s_waitcnt lgkmcnt(6)
	v_add_f32_e32 v177, v177, v185
	s_waitcnt lgkmcnt(5)
	v_add_f32_e32 v184, v178, v186
	s_waitcnt lgkmcnt(4)
	v_add_f32_e32 v185, v179, v187
	s_waitcnt lgkmcnt(3)
	v_add_f32_e32 v186, v180, v188
	s_waitcnt lgkmcnt(2)
	v_add_f32_e32 v187, v181, v189
	s_waitcnt lgkmcnt(1)
	v_add_f32_e32 v188, v182, v190
	s_waitcnt lgkmcnt(0)
	v_add_f32_e32 v189, v183, v191
	ds_bpermute_b32 v178, v213, v176
	ds_bpermute_b32 v179, v213, v177
	ds_bpermute_b32 v180, v213, v184
	ds_bpermute_b32 v181, v213, v185
	ds_bpermute_b32 v182, v213, v186
	ds_bpermute_b32 v183, v213, v187
	ds_bpermute_b32 v190, v213, v188
	ds_bpermute_b32 v191, v213, v189
	s_waitcnt lgkmcnt(7)
	v_add_f32_e32 v178, v176, v178
	s_waitcnt lgkmcnt(6)
	v_add_f32_e32 v179, v177, v179
	s_waitcnt lgkmcnt(5)
	v_add_f32_e32 v180, v184, v180
	s_waitcnt lgkmcnt(4)
	v_add_f32_e32 v181, v185, v181
	s_waitcnt lgkmcnt(3)
	v_add_f32_e32 v182, v186, v182
	s_waitcnt lgkmcnt(2)
	v_add_f32_e32 v183, v187, v183
	s_waitcnt lgkmcnt(1)
	v_add_f32_e32 v185, v188, v190
	s_waitcnt lgkmcnt(0)
	v_add_f32_e32 v187, v189, v191
	ds_bpermute_b32 v184, v214, v178
	ds_bpermute_b32 v186, v214, v179
	ds_bpermute_b32 v188, v214, v180
	ds_bpermute_b32 v189, v214, v181
	ds_bpermute_b32 v190, v214, v182
	ds_bpermute_b32 v191, v214, v183
	ds_bpermute_b32 v205, v214, v185
	ds_bpermute_b32 v206, v214, v187
	v_and_or_b32 v176, s0, -8, v192
	v_ashrrev_i32_e32 v177, 31, v176
	v_lshlrev_b64 v[176:177], 16, v[176:177]
	v_lshl_add_u64 v[176:177], s[26:27], 0, v[176:177]
	s_and_saveexec_b64 s[0:1], s[4:5]
	s_cbranch_execz .LBB0_224
; DI float log_sigmoid_f(float z) { return fminf(z, 0.f) - log1pf(__expf(-fabsf(z))); }
; DI void p0_row(const Params& P, int row, const f32x4 (&v)[4], bf16_t* U, float* LOGF, const LAS f32x4* wf, int lane) {
;     ...
;     for (int j = 0; j < 8; ++j) { const float s = wave_sum(acc[j]); if (lane == j) mine = s; }
;     if (lane < 8) { const int b = row >> 14, t = row & (SEQ - 1); LOGF[(size_t)(b * 8 + lane) * SEQ + t] = log_sigmoid_f(mine + P.b_f[lane]); }
	global_load_dword v207, v[198:199], off
	s_waitcnt lgkmcnt(7)
	v_add_f32_e32 v178, v178, v184
	s_waitcnt lgkmcnt(6)
	v_add_f32_e32 v179, v179, v186
	v_cndmask_b32_e64 v178, 0, v178, s[20:21]
	s_waitcnt lgkmcnt(5)
	v_add_f32_e32 v180, v180, v188
	v_cndmask_b32_e64 v178, v178, v179, s[18:19]
	s_waitcnt lgkmcnt(4)
	v_add_f32_e32 v181, v181, v189
	v_cndmask_b32_e64 v178, v178, v180, s[16:17]
	s_waitcnt lgkmcnt(3)
	v_add_f32_e32 v182, v182, v190
	v_cndmask_b32_e64 v178, v178, v181, s[14:15]
	s_waitcnt lgkmcnt(2)
	v_add_f32_e32 v183, v183, v191
	v_cndmask_b32_e64 v178, v178, v182, s[12:13]
	s_waitcnt lgkmcnt(1)
	v_add_f32_e32 v185, v185, v205
	v_cndmask_b32_e64 v178, v178, v183, s[10:11]
	s_waitcnt lgkmcnt(0)
	v_add_f32_e32 v187, v187, v206
	v_cndmask_b32_e64 v178, v178, v185, s[8:9]
	v_cndmask_b32_e64 v178, v178, v187, s[6:7]
	s_and_b32 s22, s28, 0x3ffc
	s_lshl_b32 s44, s22, 2
	s_waitcnt vmcnt(0)
	v_add_f32_e32 v178, v178, v207
	v_mul_f32_e64 v179, |v178|, s29
	v_exp_f32_e32 v206, v179
	v_min_f32_e32 v207, 0, v178
	v_add_f32_e32 v180, 1.0, v206
	v_add_f32_e32 v181, -1.0, v180
	v_frexp_mant_f32_e32 v182, v180
	v_cvt_f64_f32_e32 v[178:179], v180
	v_sub_f32_e32 v183, v181, v180
	v_frexp_exp_i32_f64_e32 v178, v[178:179]
	v_cmp_gt_f32_e32 vcc, s43, v182
	v_sub_f32_e32 v181, v206, v181
	v_add_f32_e32 v179, 1.0, v183
	v_subbrev_co_u32_e32 v178, vcc, 0, v178, vcc
	v_add_f32_e32 v179, v181, v179
	v_sub_u32_e32 v181, 0, v178
	v_ldexp_f32 v180, v180, v181
	v_add_f32_e32 v182, -1.0, v180
	v_add_f32_e32 v183, 1.0, v180
	v_ldexp_f32 v179, v179, v181
	v_add_f32_e32 v181, 1.0, v182
	v_add_f32_e32 v184, -1.0, v183
	v_sub_f32_e32 v181, v180, v181
	v_sub_f32_e32 v180, v180, v184
	v_add_f32_e32 v184, v179, v181
	v_add_f32_e32 v179, v179, v180
	v_add_f32_e32 v186, v183, v179
	v_rcp_f32_e32 v187, v186
	v_add_f32_e32 v181, v182, v184
	v_sub_f32_e32 v182, v181, v182
	v_sub_f32_e32 v180, v186, v183
	v_mul_f32_e32 v189, v181, v187
	v_sub_f32_e32 v188, v184, v182
	v_mul_f32_e32 v182, v186, v189
	v_sub_f32_e32 v179, v179, v180
	v_fma_f32 v184, v189, v186, -v182
	v_fmac_f32_e32 v184, v189, v179
	v_add_f32_e32 v180, v182, v184
	v_sub_f32_e32 v183, v181, v180
	v_mov_b32_e32 v185, v180
	v_pk_add_f32 v[180:181], v[180:181], v[182:183] neg_lo:[0,1] neg_hi:[0,1]
	v_cvt_f32_i32_e32 v178, v178
	v_pk_add_f32 v[180:181], v[180:181], v[184:185] neg_lo:[0,1] neg_hi:[0,1]
	v_cmp_neq_f32_e32 vcc, s53, v206
	v_add_f32_e32 v181, v188, v181
	v_add_f32_e32 v180, v180, v181
	v_add_f32_e32 v181, v183, v180
	v_mul_f32_e32 v185, v187, v181
	v_mul_f32_e32 v182, v186, v185
	v_sub_f32_e32 v183, v183, v181
	v_add_f32_e32 v190, v189, v185
	v_fma_f32 v184, v185, v186, -v182
	v_add_f32_e32 v188, v180, v183
	v_sub_f32_e32 v180, v190, v189
	v_fmac_f32_e32 v184, v185, v179
	v_sub_f32_e32 v179, v185, v180
	v_add_f32_e32 v180, v182, v184
	v_sub_f32_e32 v183, v181, v180
	v_mov_b32_e32 v185, v180
	v_pk_add_f32 v[180:181], v[180:181], v[182:183] neg_lo:[0,1] neg_hi:[0,1]
	s_nop 0
	v_pk_add_f32 v[180:181], v[180:181], v[184:185] neg_lo:[0,1] neg_hi:[0,1]
	s_nop 0
	v_add_f32_e32 v181, v188, v181
	v_add_f32_e32 v180, v180, v181
	v_add_f32_e32 v180, v183, v180
	v_mul_f32_e32 v180, v187, v180
	v_add_f32_e32 v179, v179, v180
	v_add_f32_e32 v180, v190, v179
	v_mul_f32_e32 v182, v180, v180
	v_sub_f32_e32 v183, v180, v190
	v_fmamk_f32 v184, v182, 0x3e9b6dac, v217
	v_sub_f32_e32 v183, v179, v183
	v_mul_f32_e32 v179, v180, v182
	v_fmaak_f32 v205, v182, v184, 0x3f2aaada
	v_ldexp_f32 v185, v183, 1
	v_pk_mul_f32 v[182:183], v[178:179], v[204:205]
	v_ldexp_f32 v181, v180, 1
	v_fma_f32 v180, v178, s52, -v182
	v_fmac_f32_e32 v180, 0xb102e308, v178
	v_pk_add_f32 v[178:179], v[182:183], v[180:181]
	v_mov_b32_e32 v184, v182
	v_sub_f32_e32 v188, v179, v181
	v_pk_add_f32 v[186:187], v[178:179], v[182:183] neg_lo:[0,1] neg_hi:[0,1]
	v_sub_f32_e32 v182, v183, v188
	v_add_f32_e32 v185, v185, v182
	v_pk_add_f32 v[182:183], v[178:179], v[184:185]
	v_mov_b32_e32 v181, v178
	v_mov_b32_e32 v187, v183
	v_pk_add_f32 v[190:191], v[180:181], v[186:187] neg_lo:[0,1] neg_hi:[0,1]
	v_pk_add_f32 v[180:181], v[180:181], v[186:187]
	v_mov_b32_e32 v189, v178
	v_pk_add_f32 v[186:187], v[180:181], v[178:179] op_sel:[1,0] op_sel_hi:[0,1] neg_lo:[0,1] neg_hi:[0,1]
	v_mov_b32_e32 v188, v185
	v_mov_b32_e32 v184, v183
	v_mov_b32_e32 v185, v181
	v_pk_mov_b32 v[178:179], v[178:179], v[186:187] op_sel:[1,0]
	v_pk_add_f32 v[182:183], v[182:183], v[186:187] op_sel_hi:[1,0] neg_lo:[0,1] neg_hi:[0,1]
	v_pk_add_f32 v[178:179], v[184:185], v[178:179] neg_lo:[0,1] neg_hi:[0,1]
	v_mov_b32_e32 v182, v190
	v_pk_add_f32 v[178:179], v[188:189], v[178:179] neg_lo:[0,1] neg_hi:[0,1]
	v_mov_b32_e32 v191, v181
	v_pk_add_f32 v[182:183], v[182:183], v[178:179]
	s_nop 0
	v_pk_add_f32 v[184:185], v[182:183], v[182:183] op_sel:[0,1] op_sel_hi:[1,0]
	s_nop 0
	v_pk_add_f32 v[180:181], v[180:181], v[184:185] op_sel:[1,0] op_sel_hi:[0,1]
	v_mov_b32_e32 v183, v180
	v_mov_b32_e32 v179, v184
	v_pk_add_f32 v[184:185], v[182:183], v[190:191] neg_lo:[0,1] neg_hi:[0,1]
	s_nop 0
	v_sub_f32_e32 v181, v182, v184
	v_pk_add_f32 v[178:179], v[178:179], v[184:185] neg_lo:[0,1] neg_hi:[0,1]
	v_sub_f32_e32 v181, v190, v181
	v_add_f32_e32 v178, v178, v181
	v_add_f32_e32 v178, v178, v179
	v_add_f32_e32 v178, v180, v178
	v_cndmask_b32_e32 v178, v218, v178, vcc
	v_cmp_ngt_f32_e32 vcc, -1.0, v206
	s_nop 1
	v_cndmask_b32_e32 v178, v219, v178, vcc
	v_cmp_neq_f32_e32 vcc, -1.0, v206
	s_nop 1
	v_cndmask_b32_e32 v178, v220, v178, vcc
	v_cmp_lt_f32_e64 vcc, |v206|, s54
	s_nop 1
	v_cndmask_b32_e32 v178, v178, v206, vcc
	v_sub_f32_e32 v180, v207, v178
	v_lshl_add_u64 v[178:179], v[176:177], 0, s[44:45]
	global_store_dword v[178:179], v180, off
